# v23 + trailing half keeps priority 1 through its run-ahead QK^T block (drops to 0 right before its barrier)
# speedup vs baseline: 1.0039x; 1.0039x over previous
.LqT_rest:
	v_add_u32_e32 v116, s54, v214
	v_add_u32_e32 v216, v116, v157
	v_add_u32_e32 v218, v116, v208
	v_add_u32_e32 v217, v116, v193
	v_add_u32_e32 v219, v116, v209
	v_mfma_f32_32x32x16_bf16 v[64:79], v[136:139], v[104:107], v[64:79]
	v_mfma_f32_32x32x16_bf16 v[80:95], v[120:123], v[104:107], v[80:95]
	v_mfma_f32_32x32x16_bf16 v[64:79], v[140:143], v[100:103], v[64:79]
	v_mfma_f32_32x32x16_bf16 v[80:95], v[124:127], v[100:103], v[80:95]
	v_mfma_f32_32x32x16_bf16 v[80:95], v[112:115], v[96:99], v[80:95]
	ds_read_b128 v[242:245], v216 offset:16384
	ds_read_b128 v[246:249], v216 offset:20480
	ds_read_b128 v[250:253], v216 offset:24576
	ds_read_b128 v[200:203], v216 offset:28672
	ds_read_b128 v[220:223], v217 offset:16384
	ds_read_b128 v[224:227], v217 offset:20480
	ds_read_b128 v[234:237], v217 offset:24576
	ds_read_b128 v[238:241], v217 offset:28672
	v_mfma_f32_32x32x16_bf16 v[64:79], v[128:131], v[96:99], v[64:79]
	s_setprio 0
	s_cmp_eq_u32 s33, 0
	s_cbranch_scc1 .LqT_xt
	s_barrier

.LqT_g0:
	v_exp_f32_e32 v64, v64
	v_exp_f32_e32 v65, v65
	v_exp_f32_e32 v66, v66
	v_exp_f32_e32 v67, v67
	v_add_f32_e32 v184, v64, v65
	v_exp_f32_e32 v68, v68
	v_exp_f32_e32 v69, v69
	v_cvt_pk_bf16_f32 v64, v64, v65
	v_add_f32_e32 v185, v66, v67
	v_cvt_pk_bf16_f32 v65, v66, v67
	v_exp_f32_e32 v70, v70
	v_exp_f32_e32 v71, v71
	v_add_f32_e32 v186, v68, v69
	v_cvt_pk_bf16_f32 v66, v68, v69
	v_add_f32_e32 v184, v184, v185
	v_add_f32_e32 v187, v70, v71
	v_cvt_pk_bf16_f32 v67, v70, v71
	v_add_f32_e32 v186, v186, v187
	v_add_f32_e32 v184, v184, v186
	v_add_f32_e32 v206, v206, v184
	s_waitcnt vmcnt(0) lgkmcnt(0)
	s_add_i32 s54, s33, 1
	s_setprio 1
	v_mfma_f32_32x32x16_bf16 v[32:47], v[242:245], v[64:67], v[32:47]
	v_exp_f32_e32 v72, v72
	v_exp_f32_e32 v73, v73
	v_exp_f32_e32 v74, v74
	v_exp_f32_e32 v75, v75
	v_add_f32_e32 v184, v72, v73
	s_and_b32 s100, s65, 0x18000
	v_add_u32_e32 v194, s100, v149
	v_add_u32_e32 v195, v194, v157
	v_add_u32_e32 v196, v194, v193
	ds_read_b128 v[242:245], v218 offset:16384
	v_mfma_f32_32x32x16_bf16 v[48:63], v[246:249], v[64:67], v[48:63]
	v_exp_f32_e32 v76, v76
	v_exp_f32_e32 v77, v77
	v_cvt_pk_bf16_f32 v68, v72, v73
	v_add_f32_e32 v185, v74, v75
	v_cvt_pk_bf16_f32 v69, v74, v75
	v_add_u32_e32 v197, v194, v208
	v_add_u32_e32 v194, v194, v209
	ds_read_b128 v[132:135], v195
	ds_read_b128 v[116:119], v195 offset:4096
	ds_read_b128 v[246:249], v218 offset:20480
	v_mfma_f32_32x32x16_bf16 v[16:31], v[250:253], v[64:67], v[16:31]
	v_exp_f32_e32 v78, v78
	v_exp_f32_e32 v79, v79
	v_add_f32_e32 v186, v76, v77
	v_cvt_pk_bf16_f32 v70, v76, v77
	v_add_f32_e32 v184, v184, v185
	ds_read_b128 v[136:139], v196
	ds_read_b128 v[120:123], v196 offset:4096
	ds_read_b128 v[140:143], v197
	ds_read_b128 v[124:127], v197 offset:4096
	ds_read_b128 v[250:253], v218 offset:24576
	v_mfma_f32_32x32x16_bf16 v[0:15], v[200:203], v[64:67], v[0:15]
	v_add_f32_e32 v187, v78, v79
	v_cvt_pk_bf16_f32 v71, v78, v79
	v_add_f32_e32 v186, v186, v187
	v_add_f32_e32 v184, v184, v186
	v_add_f32_e32 v206, v206, v184
	ds_read_b128 v[128:131], v194
	ds_read_b128 v[112:115], v194 offset:4096
	ds_read_b128 v[200:203], v218 offset:28672
	v_mfma_f32_32x32x16_bf16 v[32:47], v[220:223], v[68:71], v[32:47]
	v_exp_f32_e32 v80, v80
	v_exp_f32_e32 v81, v81
	v_exp_f32_e32 v82, v82
	v_exp_f32_e32 v83, v83
	v_add_f32_e32 v184, v80, v81
	ds_read_b128 v[220:223], v219 offset:16384
	v_mfma_f32_32x32x16_bf16 v[48:63], v[224:227], v[68:71], v[48:63]
	v_exp_f32_e32 v84, v84
	v_exp_f32_e32 v85, v85
	v_cvt_pk_bf16_f32 v72, v80, v81
	v_add_f32_e32 v185, v82, v83
	v_cvt_pk_bf16_f32 v73, v82, v83
	ds_read_b128 v[224:227], v219 offset:20480
	v_mfma_f32_32x32x16_bf16 v[16:31], v[234:237], v[68:71], v[16:31]
	v_exp_f32_e32 v86, v86
	v_exp_f32_e32 v87, v87
	v_add_f32_e32 v186, v84, v85
	v_cvt_pk_bf16_f32 v74, v84, v85
	v_add_f32_e32 v184, v184, v185
	ds_read_b128 v[234:237], v219 offset:24576
	v_mfma_f32_32x32x16_bf16 v[0:15], v[238:241], v[68:71], v[0:15]
	v_add_f32_e32 v187, v86, v87
	v_cvt_pk_bf16_f32 v75, v86, v87
	v_add_f32_e32 v186, v186, v187
	v_add_f32_e32 v184, v184, v186
	v_add_f32_e32 v206, v206, v184
	ds_read_b128 v[238:241], v219 offset:28672
	s_waitcnt lgkmcnt(4)
	v_mfma_f32_32x32x16_bf16 v[32:47], v[242:245], v[72:75], v[32:47]
	v_exp_f32_e32 v88, v88
	v_exp_f32_e32 v89, v89
	v_exp_f32_e32 v90, v90
	v_exp_f32_e32 v91, v91
	v_add_f32_e32 v184, v88, v89
	v_mfma_f32_32x32x16_bf16 v[48:63], v[246:249], v[72:75], v[48:63]
	v_exp_f32_e32 v92, v92
	v_exp_f32_e32 v93, v93
	v_cvt_pk_bf16_f32 v76, v88, v89
	v_add_f32_e32 v185, v90, v91
	v_cvt_pk_bf16_f32 v77, v90, v91
	v_mfma_f32_32x32x16_bf16 v[16:31], v[250:253], v[72:75], v[16:31]
	v_exp_f32_e32 v94, v94
	v_exp_f32_e32 v95, v95
	v_add_f32_e32 v186, v92, v93
	v_cvt_pk_bf16_f32 v78, v92, v93
	v_add_f32_e32 v184, v184, v185
	v_mfma_f32_32x32x16_bf16 v[0:15], v[200:203], v[72:75], v[0:15]
	v_add_f32_e32 v187, v94, v95
	v_cvt_pk_bf16_f32 v79, v94, v95
	v_add_f32_e32 v186, v186, v187
	v_add_f32_e32 v184, v184, v186
	v_add_f32_e32 v206, v206, v184
	s_waitcnt lgkmcnt(0)
	v_mfma_f32_32x32x16_bf16 v[32:47], v[220:223], v[76:79], v[32:47]
	v_mfma_f32_32x32x16_bf16 v[48:63], v[224:227], v[76:79], v[48:63]
	s_waitcnt lgkmcnt(0)
	s_add_i32 s65, s65, 0x8000
	s_addk_i32 s23, 0x100
	s_add_i32 s36, s36, 64
	s_mov_b32 s33, s54
	s_cmpk_eq_i32 s23, 0x1e00
	v_mfma_f32_32x32x16_bf16 v[16:31], v[234:237], v[76:79], v[16:31]
	v_mfma_f32_32x32x16_bf16 v[0:15], v[238:241], v[76:79], v[0:15]
	s_cbranch_scc0 .LqT_top
	s_barrier
	s_branch .LBB0_284
